# P6F fused epilogue: all 16 residual loads prefetched up front with counted vmcnt
# baseline (speedup 1.0000x reference)
.LBB0_1376:
	s_lshl_b32 s18, s8, 8
	s_add_i32 s2, s18, s62
	v_or_b32_e32 v166, s2, v3
	s_lshl_b32 s2, s0, 8
	s_lshl_b32 s3, s9, 6
	s_or_b32 s2, s2, s3
	v_ashrrev_i32_e32 v167, 31, v166
	v_lshl_or_b32 v0, v142, 3, s2
	v_cmp_gt_u32_e64 s[2:3], 8, v3
	v_mov_b32_e32 v3, 0xffffc040
	v_lshlrev_b64 v[132:133], 11, v[166:167]
	v_ashrrev_i32_e32 v1, 31, v0
	v_cndmask_b32_e64 v162, v3, 0, s[2:3]
	v_mov_b32_e32 v3, 0x4040
	v_lshl_add_u64 v[132:133], s[42:43], 0, v[132:133]
	v_cndmask_b32_e64 v163, -1, 0, s[2:3]
	v_cndmask_b32_e64 v164, 0, v3, s[2:3]
	v_mov_b32_e32 v165, 0
	v_lshl_add_u64 v[132:133], v[0:1], 1, v[132:133]
	v_lshl_add_u64 v[236:237], v[132:133], 0, v[162:163]
	v_lshl_add_u64 v[238:239], v[132:133], 0, v[164:165]
	global_load_dwordx4 v[172:175], v[236:237], off
	global_load_dwordx4 v[176:179], v[238:239], off
	s_mov_b64 s[4:5], 0x8000
	v_lshl_add_u64 v[240:241], v[236:237], 0, s[4:5]
	v_lshl_add_u64 v[242:243], v[238:239], 0, s[4:5]
	global_load_dwordx4 v[180:183], v[240:241], off
	global_load_dwordx4 v[184:187], v[242:243], off
	s_mov_b64 s[4:5], 0x10000
	v_lshl_add_u64 v[240:241], v[236:237], 0, s[4:5]
	v_lshl_add_u64 v[242:243], v[238:239], 0, s[4:5]
	global_load_dwordx4 v[188:191], v[240:241], off
	global_load_dwordx4 v[192:195], v[242:243], off
	s_mov_b64 s[4:5], 0x18000
	v_lshl_add_u64 v[240:241], v[236:237], 0, s[4:5]
	v_lshl_add_u64 v[242:243], v[238:239], 0, s[4:5]
	global_load_dwordx4 v[196:199], v[240:241], off
	global_load_dwordx4 v[200:203], v[242:243], off
	s_mov_b64 s[4:5], 0x40000
	v_lshl_add_u64 v[240:241], v[236:237], 0, s[4:5]
	v_lshl_add_u64 v[242:243], v[238:239], 0, s[4:5]
	global_load_dwordx4 v[204:207], v[240:241], off
	global_load_dwordx4 v[208:211], v[242:243], off
	s_mov_b64 s[4:5], 0x48000
	v_lshl_add_u64 v[240:241], v[236:237], 0, s[4:5]
	v_lshl_add_u64 v[242:243], v[238:239], 0, s[4:5]
	global_load_dwordx4 v[212:215], v[240:241], off
	global_load_dwordx4 v[216:219], v[242:243], off
	s_mov_b64 s[4:5], 0x50000
	v_lshl_add_u64 v[240:241], v[236:237], 0, s[4:5]
	v_lshl_add_u64 v[242:243], v[238:239], 0, s[4:5]
	global_load_dwordx4 v[220:223], v[240:241], off
	global_load_dwordx4 v[224:227], v[242:243], off
	s_mov_b64 s[4:5], 0x58000
	v_lshl_add_u64 v[240:241], v[236:237], 0, s[4:5]
	v_lshl_add_u64 v[242:243], v[238:239], 0, s[4:5]
	global_load_dwordx4 v[228:231], v[240:241], off
	global_load_dwordx4 v[232:235], v[242:243], off
	v_lshl_add_u64 v[134:135], v[132:133], 0, v[162:163]
	v_lshl_add_u64 v[136:137], v[132:133], 0, v[164:165]
	s_barrier
	v_mbcnt_lo_u32_b32 v3, -1, 0
	v_mbcnt_hi_u32_b32 v3, -1, v3
	v_and_b32_e32 v145, 64, v3
	v_xor_b32_e32 v144, 16, v3
	v_add_u32_e32 v170, 64, v145
	v_cmp_lt_i32_e32 vcc, v144, v170
	v_mov_b32_e32 v140, v165
	v_mov_b32_e32 v141, v165
	v_cndmask_b32_e32 v144, v3, v144, vcc
	v_lshlrev_b32_e32 v169, 2, v144
	v_mov_b32_e32 v142, v165
	v_mov_b32_e32 v143, v165
	s_lshl_b32 s4, s9, 2
	s_add_i32 s6, s4, 0x100
	s_waitcnt vmcnt(14)
	v_cndmask_b32_e64 v144, v176, v172, s[2:3]
	v_cndmask_b32_e64 v145, v177, v173, s[2:3]
	v_cndmask_b32_e64 v146, v178, v174, s[2:3]
	v_cndmask_b32_e64 v147, v179, v175, s[2:3]
	v_cndmask_b32_e64 v132, v172, v176, s[2:3]
	v_cndmask_b32_e64 v133, v173, v177, s[2:3]
	v_cndmask_b32_e64 v134, v174, v178, s[2:3]
	v_cndmask_b32_e64 v135, v175, v179, s[2:3]
	v_mov_b32_dpp v140, v132 row_ror:8 row_mask:0xf bank_mask:0xf
	v_mov_b32_dpp v141, v133 row_ror:8 row_mask:0xf bank_mask:0xf
	v_lshlrev_b32_e32 v136, 16, v146
	v_and_b32_e32 v137, 0xffff0000, v146
	v_lshlrev_b32_e32 v138, 16, v147
	v_and_b32_e32 v139, 0xffff0000, v147
	v_mov_b32_dpp v142, v134 row_ror:8 row_mask:0xf bank_mask:0xf
	v_mov_b32_dpp v143, v135 row_ror:8 row_mask:0xf bank_mask:0xf
	v_lshlrev_b32_e32 v132, 16, v144
	v_and_b32_e32 v133, 0xffff0000, v144
	v_lshlrev_b32_e32 v134, 16, v145
	v_and_b32_e32 v135, 0xffff0000, v145
	v_pk_add_f32 v[152:153], v[126:127], v[138:139]
	v_pk_add_f32 v[154:155], v[124:125], v[136:137]
	v_lshlrev_b32_e32 v124, 16, v140
	v_and_b32_e32 v125, 0xffff0000, v140
	v_lshlrev_b32_e32 v126, 16, v141
	v_and_b32_e32 v127, 0xffff0000, v141
	v_pk_add_f32 v[158:159], v[130:131], v[134:135]
	v_pk_add_f32 v[160:161], v[128:129], v[132:133]
	v_lshlrev_b32_e32 v128, 16, v142
	v_and_b32_e32 v129, 0xffff0000, v142
	v_pk_add_f32 v[148:149], v[122:123], v[126:127]
	v_pk_add_f32 v[150:151], v[120:121], v[124:125]
	v_lshlrev_b32_e32 v130, 16, v143
	v_and_b32_e32 v131, 0xffff0000, v143
	v_mul_f32_e32 v132, v161, v161
	v_mul_f32_e32 v133, v159, v159
	v_pk_add_f32 v[146:147], v[116:117], v[128:129]
	v_mul_f32_e32 v116, v151, v151
	v_mul_f32_e32 v117, v149, v149
	v_mul_f32_e32 v134, v155, v155
	v_pk_add_f32 v[144:145], v[118:119], v[130:131]
	v_fmac_f32_e32 v132, v160, v160
	v_fmac_f32_e32 v133, v158, v158
	v_mul_f32_e32 v118, v147, v147
	v_fmac_f32_e32 v116, v150, v150
	v_fmac_f32_e32 v117, v148, v148
	v_mul_f32_e32 v135, v153, v153
	v_fmac_f32_e32 v134, v154, v154
	v_mul_f32_e32 v119, v145, v145
	v_add_f32_e32 v120, v132, v133
	v_fmac_f32_e32 v118, v146, v146
	v_add_f32_e32 v116, v116, v117
	v_fmac_f32_e32 v135, v152, v152
	v_add_f32_e32 v120, v134, v120
	v_add_f32_e32 v116, v116, v118
	v_fmac_f32_e32 v119, v144, v144
	v_add_f32_e32 v117, v135, v120
	v_add_f32_e32 v116, v119, v116
	v_add_f32_e32 v116, v116, v117
	ds_bpermute_b32 v117, v169, v116
	v_xor_b32_e32 v118, 32, v3
	v_cmp_lt_i32_e32 vcc, v118, v170
	v_lshl_add_u32 v170, v168, 4, s6
	s_nop 0
	v_cndmask_b32_e32 v3, v3, v118, vcc
	v_lshlrev_b32_e32 v171, 2, v3
	s_waitcnt lgkmcnt(0)
	v_add_f32_e32 v3, v116, v117
	ds_bpermute_b32 v116, v171, v3
	v_cmp_gt_u32_e32 vcc, 16, v157
	s_and_saveexec_b64 s[4:5], vcc
	v_readlane_b32 s22, v254, 13
	v_readlane_b32 s23, v254, 14
	s_cbranch_execz .LBB0_1378
	s_waitcnt lgkmcnt(0)
	v_add_f32_e32 v3, v3, v116
	ds_write_b32 v170, v3
.LBB0_1378:
	s_or_b64 exec, exec, s[4:5]
	s_waitcnt lgkmcnt(0)
	v_or_b32_e32 v116, 16, v166
	v_ashrrev_i32_e32 v117, 31, v116
	v_lshlrev_b64 v[116:117], 11, v[116:117]
	v_lshl_add_u64 v[116:117], s[42:43], 0, v[116:117]
	v_lshl_add_u64 v[116:117], v[0:1], 1, v[116:117]
	v_lshl_add_u64 v[118:119], v[116:117], 0, v[162:163]
	v_lshl_add_u64 v[120:121], v[116:117], 0, v[164:165]
	v_mov_b32_e32 v3, v165
	v_mov_b32_e32 v124, v165
	v_mov_b32_e32 v125, v165
	v_mov_b32_e32 v126, v165
	s_waitcnt vmcnt(12)
	v_cndmask_b32_e64 v127, v184, v180, s[2:3]
	v_cndmask_b32_e64 v128, v185, v181, s[2:3]
	v_cndmask_b32_e64 v129, v186, v182, s[2:3]
	v_cndmask_b32_e64 v130, v187, v183, s[2:3]
	v_cndmask_b32_e64 v116, v180, v184, s[2:3]
	v_cndmask_b32_e64 v117, v181, v185, s[2:3]
	v_cndmask_b32_e64 v118, v182, v186, s[2:3]
	v_cndmask_b32_e64 v119, v183, v187, s[2:3]
	v_mov_b32_dpp v3, v116 row_ror:8 row_mask:0xf bank_mask:0xf
	v_mov_b32_dpp v124, v117 row_ror:8 row_mask:0xf bank_mask:0xf
	v_lshlrev_b32_e32 v120, 16, v129
	v_and_b32_e32 v121, 0xffff0000, v129
	v_lshlrev_b32_e32 v122, 16, v130
	v_and_b32_e32 v123, 0xffff0000, v130
	v_mov_b32_dpp v125, v118 row_ror:8 row_mask:0xf bank_mask:0xf
	v_mov_b32_dpp v126, v119 row_ror:8 row_mask:0xf bank_mask:0xf
	v_lshlrev_b32_e32 v116, 16, v127
	v_and_b32_e32 v117, 0xffff0000, v127
	v_lshlrev_b32_e32 v118, 16, v128
	v_and_b32_e32 v119, 0xffff0000, v128
	v_pk_add_f32 v[136:137], v[110:111], v[122:123]
	v_pk_add_f32 v[138:139], v[108:109], v[120:121]
	v_lshlrev_b32_e32 v108, 16, v3
	v_and_b32_e32 v109, 0xffff0000, v3
	v_lshlrev_b32_e32 v110, 16, v124
	v_and_b32_e32 v111, 0xffff0000, v124
	v_pk_add_f32 v[140:141], v[114:115], v[118:119]
	v_pk_add_f32 v[142:143], v[112:113], v[116:117]
	v_lshlrev_b32_e32 v112, 16, v125
	v_and_b32_e32 v113, 0xffff0000, v125
	v_pk_add_f32 v[132:133], v[106:107], v[110:111]
	v_pk_add_f32 v[134:135], v[104:105], v[108:109]
	v_lshlrev_b32_e32 v114, 16, v126
	v_and_b32_e32 v115, 0xffff0000, v126
	v_mul_f32_e32 v3, v143, v143
	v_mul_f32_e32 v116, v141, v141
	v_pk_add_f32 v[130:131], v[100:101], v[112:113]
	v_mul_f32_e32 v100, v135, v135
	v_mul_f32_e32 v101, v133, v133
	v_mul_f32_e32 v117, v139, v139
	v_pk_add_f32 v[126:127], v[102:103], v[114:115]
	v_fmac_f32_e32 v3, v142, v142
	v_fmac_f32_e32 v116, v140, v140
	v_mul_f32_e32 v102, v131, v131
	v_fmac_f32_e32 v100, v134, v134
	v_fmac_f32_e32 v101, v132, v132
	v_mul_f32_e32 v118, v137, v137
	v_fmac_f32_e32 v117, v138, v138
	v_mul_f32_e32 v103, v127, v127
	v_add_f32_e32 v3, v3, v116
	v_fmac_f32_e32 v102, v130, v130
	v_add_f32_e32 v100, v100, v101
	v_fmac_f32_e32 v118, v136, v136
	v_add_f32_e32 v3, v117, v3
	v_add_f32_e32 v100, v100, v102
	v_fmac_f32_e32 v103, v126, v126
	v_add_f32_e32 v3, v118, v3
	v_add_f32_e32 v100, v103, v100
	v_add_f32_e32 v3, v100, v3
	ds_bpermute_b32 v100, v169, v3
	s_waitcnt lgkmcnt(0)
	v_add_f32_e32 v3, v3, v100
	ds_bpermute_b32 v100, v171, v3
	s_and_saveexec_b64 s[4:5], vcc
	s_cbranch_execz .LBB0_1380
	s_waitcnt lgkmcnt(0)
	v_add_f32_e32 v3, v3, v100
	ds_write_b32 v170, v3 offset:256
.LBB0_1380:
	s_or_b64 exec, exec, s[4:5]
	s_waitcnt lgkmcnt(0)
	v_or_b32_e32 v100, 32, v166
	v_ashrrev_i32_e32 v101, 31, v100
	v_lshlrev_b64 v[100:101], 11, v[100:101]
	v_lshl_add_u64 v[100:101], s[42:43], 0, v[100:101]
	v_lshl_add_u64 v[100:101], v[0:1], 1, v[100:101]
	v_lshl_add_u64 v[102:103], v[100:101], 0, v[162:163]
	v_lshl_add_u64 v[104:105], v[100:101], 0, v[164:165]
	v_mov_b32_e32 v3, 0
	v_mov_b32_e32 v108, 0
	v_mov_b32_e32 v109, 0
	v_mov_b32_e32 v110, 0
	s_waitcnt vmcnt(10)
	v_cndmask_b32_e64 v111, v192, v188, s[2:3]
	v_cndmask_b32_e64 v112, v193, v189, s[2:3]
	v_cndmask_b32_e64 v113, v194, v190, s[2:3]
	v_cndmask_b32_e64 v114, v195, v191, s[2:3]
	v_cndmask_b32_e64 v100, v188, v192, s[2:3]
	v_cndmask_b32_e64 v101, v189, v193, s[2:3]
	v_cndmask_b32_e64 v102, v190, v194, s[2:3]
	v_cndmask_b32_e64 v103, v191, v195, s[2:3]
	v_mov_b32_dpp v3, v100 row_ror:8 row_mask:0xf bank_mask:0xf
	v_mov_b32_dpp v108, v101 row_ror:8 row_mask:0xf bank_mask:0xf
	v_lshlrev_b32_e32 v104, 16, v113
	v_and_b32_e32 v105, 0xffff0000, v113
	v_lshlrev_b32_e32 v106, 16, v114
	v_and_b32_e32 v107, 0xffff0000, v114
	v_mov_b32_dpp v109, v102 row_ror:8 row_mask:0xf bank_mask:0xf
	v_mov_b32_dpp v110, v103 row_ror:8 row_mask:0xf bank_mask:0xf
	v_lshlrev_b32_e32 v100, 16, v111
	v_and_b32_e32 v101, 0xffff0000, v111
	v_lshlrev_b32_e32 v102, 16, v112
	v_and_b32_e32 v103, 0xffff0000, v112
	v_pk_add_f32 v[120:121], v[94:95], v[106:107]
	v_pk_add_f32 v[122:123], v[92:93], v[104:105]
	v_lshlrev_b32_e32 v92, 16, v3
	v_and_b32_e32 v93, 0xffff0000, v3
	v_lshlrev_b32_e32 v94, 16, v108
	v_and_b32_e32 v95, 0xffff0000, v108
	v_pk_add_f32 v[124:125], v[98:99], v[102:103]
	v_pk_add_f32 v[128:129], v[96:97], v[100:101]
	v_lshlrev_b32_e32 v96, 16, v109
	v_and_b32_e32 v97, 0xffff0000, v109
	v_pk_add_f32 v[116:117], v[90:91], v[94:95]
	v_pk_add_f32 v[118:119], v[88:89], v[92:93]
	v_lshlrev_b32_e32 v98, 16, v110
	v_and_b32_e32 v99, 0xffff0000, v110
	v_mul_f32_e32 v3, v129, v129
	v_mul_f32_e32 v100, v125, v125
	v_pk_add_f32 v[114:115], v[84:85], v[96:97]
	v_mul_f32_e32 v84, v119, v119
	v_mul_f32_e32 v85, v117, v117
	v_mul_f32_e32 v101, v123, v123
	v_pk_add_f32 v[112:113], v[86:87], v[98:99]
	v_fmac_f32_e32 v3, v128, v128
	v_fmac_f32_e32 v100, v124, v124
	v_mul_f32_e32 v86, v115, v115
	v_fmac_f32_e32 v84, v118, v118
	v_fmac_f32_e32 v85, v116, v116
	v_mul_f32_e32 v102, v121, v121
	v_fmac_f32_e32 v101, v122, v122
	v_mul_f32_e32 v87, v113, v113
	v_add_f32_e32 v3, v3, v100
	v_fmac_f32_e32 v86, v114, v114
	v_add_f32_e32 v84, v84, v85
	v_fmac_f32_e32 v102, v120, v120
	v_add_f32_e32 v3, v101, v3
	v_add_f32_e32 v84, v84, v86
	v_fmac_f32_e32 v87, v112, v112
	v_add_f32_e32 v3, v102, v3
	v_add_f32_e32 v84, v87, v84
	v_add_f32_e32 v3, v84, v3
	ds_bpermute_b32 v84, v169, v3
	s_waitcnt lgkmcnt(0)
	v_add_f32_e32 v84, v3, v84
	ds_bpermute_b32 v85, v171, v84
	v_mov_b32_e32 v3, 0
	s_and_saveexec_b64 s[4:5], vcc
	s_cbranch_execz .LBB0_1382
	s_waitcnt lgkmcnt(0)
	v_add_f32_e32 v84, v84, v85
	ds_write_b32 v170, v84 offset:512
.LBB0_1382:
	s_or_b64 exec, exec, s[4:5]
	v_or_b32_e32 v84, 48, v166
	s_waitcnt lgkmcnt(0)
	v_ashrrev_i32_e32 v85, 31, v84
	v_lshlrev_b64 v[84:85], 11, v[84:85]
	v_lshl_add_u64 v[84:85], s[42:43], 0, v[84:85]
	v_lshl_add_u64 v[84:85], v[0:1], 1, v[84:85]
	v_lshl_add_u64 v[86:87], v[84:85], 0, v[162:163]
	v_lshl_add_u64 v[88:89], v[84:85], 0, v[164:165]
	v_mov_b32_e32 v92, 0
	v_mov_b32_e32 v93, 0
	v_mov_b32_e32 v94, 0
	s_waitcnt vmcnt(8)
	v_cndmask_b32_e64 v95, v200, v196, s[2:3]
	v_cndmask_b32_e64 v96, v201, v197, s[2:3]
	v_cndmask_b32_e64 v97, v202, v198, s[2:3]
	v_cndmask_b32_e64 v98, v203, v199, s[2:3]
	v_cndmask_b32_e64 v84, v196, v200, s[2:3]
	v_cndmask_b32_e64 v85, v197, v201, s[2:3]
	v_cndmask_b32_e64 v86, v198, v202, s[2:3]
	v_cndmask_b32_e64 v87, v199, v203, s[2:3]
	v_mov_b32_dpp v92, v84 row_ror:8 row_mask:0xf bank_mask:0xf
	v_mov_b32_dpp v93, v85 row_ror:8 row_mask:0xf bank_mask:0xf
	v_lshlrev_b32_e32 v88, 16, v97
	v_and_b32_e32 v89, 0xffff0000, v97
	v_lshlrev_b32_e32 v90, 16, v98
	v_and_b32_e32 v91, 0xffff0000, v98
	v_mov_b32_dpp v94, v86 row_ror:8 row_mask:0xf bank_mask:0xf
	v_mov_b32_dpp v3, v87 row_ror:8 row_mask:0xf bank_mask:0xf
	v_lshlrev_b32_e32 v84, 16, v95
	v_and_b32_e32 v85, 0xffff0000, v95
	v_lshlrev_b32_e32 v86, 16, v96
	v_and_b32_e32 v87, 0xffff0000, v96
	v_pk_add_f32 v[104:105], v[78:79], v[90:91]
	v_pk_add_f32 v[106:107], v[76:77], v[88:89]
	v_lshlrev_b32_e32 v76, 16, v92
	v_and_b32_e32 v77, 0xffff0000, v92
	v_lshlrev_b32_e32 v78, 16, v93
	v_and_b32_e32 v79, 0xffff0000, v93
	v_pk_add_f32 v[108:109], v[82:83], v[86:87]
	v_pk_add_f32 v[110:111], v[80:81], v[84:85]
	v_lshlrev_b32_e32 v80, 16, v94
	v_and_b32_e32 v81, 0xffff0000, v94
	v_pk_add_f32 v[100:101], v[74:75], v[78:79]
	v_pk_add_f32 v[102:103], v[72:73], v[76:77]
	v_lshlrev_b32_e32 v82, 16, v3
	v_and_b32_e32 v83, 0xffff0000, v3
	v_mul_f32_e32 v3, v111, v111
	v_mul_f32_e32 v84, v109, v109
	v_pk_add_f32 v[98:99], v[68:69], v[80:81]
	v_mul_f32_e32 v68, v103, v103
	v_mul_f32_e32 v69, v101, v101
	v_mul_f32_e32 v85, v107, v107
	v_pk_add_f32 v[94:95], v[70:71], v[82:83]
	v_fmac_f32_e32 v3, v110, v110
	v_fmac_f32_e32 v84, v108, v108
	v_mul_f32_e32 v70, v99, v99
	v_fmac_f32_e32 v68, v102, v102
	v_fmac_f32_e32 v69, v100, v100
	v_mul_f32_e32 v86, v105, v105
	v_fmac_f32_e32 v85, v106, v106
	v_mul_f32_e32 v71, v95, v95
	v_add_f32_e32 v3, v3, v84
	v_fmac_f32_e32 v70, v98, v98
	v_add_f32_e32 v68, v68, v69
	v_fmac_f32_e32 v86, v104, v104
	v_add_f32_e32 v3, v85, v3
	v_add_f32_e32 v68, v68, v70
	v_fmac_f32_e32 v71, v94, v94
	v_add_f32_e32 v3, v86, v3
	v_add_f32_e32 v68, v71, v68
	v_add_f32_e32 v3, v68, v3
	ds_bpermute_b32 v68, v169, v3
	s_waitcnt lgkmcnt(0)
	v_add_f32_e32 v3, v3, v68
	ds_bpermute_b32 v68, v171, v3
	s_and_saveexec_b64 s[4:5], vcc
	s_cbranch_execz .LBB0_1384
	s_waitcnt lgkmcnt(0)
	v_add_f32_e32 v3, v3, v68
	ds_write_b32 v170, v3 offset:768
.LBB0_1384:
	s_or_b64 exec, exec, s[4:5]
	s_waitcnt lgkmcnt(0)
	v_lshlrev_b64 v[68:69], 11, v[166:167]
	v_lshl_add_u64 v[68:69], s[42:43], 0, v[68:69]
	v_lshl_add_u64 v[68:69], v[0:1], 1, v[68:69]
	s_mov_b64 s[4:5], 0x40000
	v_lshl_add_u64 v[70:71], v[68:69], 0, s[4:5]
	v_lshl_add_u64 v[72:73], v[70:71], 0, v[162:163]
	v_lshl_add_u64 v[74:75], v[70:71], 0, v[164:165]
	v_mov_b32_e32 v3, 0
	v_mov_b32_e32 v78, 0
	v_mov_b32_e32 v79, 0
	v_mov_b32_e32 v80, 0
	s_waitcnt vmcnt(6)
	v_cndmask_b32_e64 v81, v208, v204, s[2:3]
	v_cndmask_b32_e64 v82, v209, v205, s[2:3]
	v_cndmask_b32_e64 v83, v210, v206, s[2:3]
	v_cndmask_b32_e64 v84, v211, v207, s[2:3]
	v_cndmask_b32_e64 v70, v204, v208, s[2:3]
	v_cndmask_b32_e64 v71, v205, v209, s[2:3]
	v_cndmask_b32_e64 v72, v206, v210, s[2:3]
	v_cndmask_b32_e64 v73, v207, v211, s[2:3]
	v_mov_b32_dpp v3, v70 row_ror:8 row_mask:0xf bank_mask:0xf
	v_mov_b32_dpp v78, v71 row_ror:8 row_mask:0xf bank_mask:0xf
	v_lshlrev_b32_e32 v74, 16, v83
	v_and_b32_e32 v75, 0xffff0000, v83
	v_lshlrev_b32_e32 v76, 16, v84
	v_and_b32_e32 v77, 0xffff0000, v84
	v_mov_b32_dpp v79, v72 row_ror:8 row_mask:0xf bank_mask:0xf
	v_mov_b32_dpp v80, v73 row_ror:8 row_mask:0xf bank_mask:0xf
	v_lshlrev_b32_e32 v70, 16, v81
	v_and_b32_e32 v71, 0xffff0000, v81
	v_lshlrev_b32_e32 v72, 16, v82
	v_and_b32_e32 v73, 0xffff0000, v82
	v_pk_add_f32 v[88:89], v[62:63], v[76:77]
	v_pk_add_f32 v[90:91], v[60:61], v[74:75]
	v_lshlrev_b32_e32 v60, 16, v3
	v_and_b32_e32 v61, 0xffff0000, v3
	v_lshlrev_b32_e32 v62, 16, v78
	v_and_b32_e32 v63, 0xffff0000, v78
	v_pk_add_f32 v[92:93], v[66:67], v[72:73]
	v_pk_add_f32 v[96:97], v[64:65], v[70:71]
	v_lshlrev_b32_e32 v64, 16, v79
	v_and_b32_e32 v65, 0xffff0000, v79
	v_pk_add_f32 v[84:85], v[58:59], v[62:63]
	v_pk_add_f32 v[86:87], v[56:57], v[60:61]
	v_lshlrev_b32_e32 v66, 16, v80
	v_and_b32_e32 v67, 0xffff0000, v80
	v_mul_f32_e32 v3, v97, v97
	v_mul_f32_e32 v70, v93, v93
	v_pk_add_f32 v[82:83], v[52:53], v[64:65]
	v_mul_f32_e32 v52, v87, v87
	v_mul_f32_e32 v53, v85, v85
	v_mul_f32_e32 v71, v91, v91
	v_pk_add_f32 v[80:81], v[54:55], v[66:67]
	v_fmac_f32_e32 v3, v96, v96
	v_fmac_f32_e32 v70, v92, v92
	v_mul_f32_e32 v54, v83, v83
	v_fmac_f32_e32 v52, v86, v86
	v_fmac_f32_e32 v53, v84, v84
	v_mul_f32_e32 v72, v89, v89
	v_fmac_f32_e32 v71, v90, v90
	v_mul_f32_e32 v55, v81, v81
	v_add_f32_e32 v3, v3, v70
	v_fmac_f32_e32 v54, v82, v82
	v_add_f32_e32 v52, v52, v53
	v_fmac_f32_e32 v72, v88, v88
	v_add_f32_e32 v3, v71, v3
	v_add_f32_e32 v52, v52, v54
	v_fmac_f32_e32 v55, v80, v80
	v_add_f32_e32 v3, v72, v3
	v_add_f32_e32 v52, v55, v52
	v_add_f32_e32 v3, v52, v3
	ds_bpermute_b32 v52, v169, v3
	s_waitcnt lgkmcnt(0)
	v_add_f32_e32 v53, v3, v52
	ds_bpermute_b32 v54, v171, v53
	v_add_u32_e32 v3, 0x80, v168
	v_mov_b32_e32 v52, 0
	s_and_saveexec_b64 s[4:5], vcc
	s_cbranch_execz .LBB0_1386
	v_lshl_add_u32 v55, v3, 4, s6
	s_waitcnt lgkmcnt(0)
	v_add_f32_e32 v53, v53, v54
	ds_write_b32 v55, v53
.LBB0_1386:
	s_or_b64 exec, exec, s[4:5]
	s_mov_b64 s[4:5], 0x48000
	s_waitcnt lgkmcnt(0)
	v_lshl_add_u64 v[54:55], v[68:69], 0, s[4:5]
	v_lshl_add_u64 v[56:57], v[54:55], 0, v[162:163]
	v_lshl_add_u64 v[58:59], v[54:55], 0, v[164:165]
	v_mov_b32_e32 v53, 0
	v_mov_b32_e32 v62, 0
	v_mov_b32_e32 v63, 0
	s_waitcnt vmcnt(4)
	v_cndmask_b32_e64 v64, v216, v212, s[2:3]
	v_cndmask_b32_e64 v65, v217, v213, s[2:3]
	v_cndmask_b32_e64 v66, v218, v214, s[2:3]
	v_cndmask_b32_e64 v67, v219, v215, s[2:3]
	v_cndmask_b32_e64 v54, v212, v216, s[2:3]
	v_cndmask_b32_e64 v55, v213, v217, s[2:3]
	v_cndmask_b32_e64 v56, v214, v218, s[2:3]
	v_cndmask_b32_e64 v57, v215, v219, s[2:3]
	v_mov_b32_dpp v53, v54 row_ror:8 row_mask:0xf bank_mask:0xf
	v_mov_b32_dpp v62, v55 row_ror:8 row_mask:0xf bank_mask:0xf
	v_lshlrev_b32_e32 v58, 16, v66
	v_and_b32_e32 v59, 0xffff0000, v66
	v_lshlrev_b32_e32 v60, 16, v67
	v_and_b32_e32 v61, 0xffff0000, v67
	v_mov_b32_dpp v63, v56 row_ror:8 row_mask:0xf bank_mask:0xf
	v_mov_b32_dpp v52, v57 row_ror:8 row_mask:0xf bank_mask:0xf
	v_lshlrev_b32_e32 v54, 16, v64
	v_and_b32_e32 v55, 0xffff0000, v64
	v_lshlrev_b32_e32 v56, 16, v65
	v_and_b32_e32 v57, 0xffff0000, v65
	v_pk_add_f32 v[72:73], v[46:47], v[60:61]
	v_pk_add_f32 v[74:75], v[44:45], v[58:59]
	v_lshlrev_b32_e32 v44, 16, v53
	v_and_b32_e32 v45, 0xffff0000, v53
	v_lshlrev_b32_e32 v46, 16, v62
	v_and_b32_e32 v47, 0xffff0000, v62
	v_pk_add_f32 v[76:77], v[50:51], v[56:57]
	v_pk_add_f32 v[78:79], v[48:49], v[54:55]
	v_lshlrev_b32_e32 v48, 16, v63
	v_and_b32_e32 v49, 0xffff0000, v63
	v_pk_add_f32 v[68:69], v[42:43], v[46:47]
	v_pk_add_f32 v[70:71], v[40:41], v[44:45]
	v_lshlrev_b32_e32 v50, 16, v52
	v_and_b32_e32 v51, 0xffff0000, v52
	v_mul_f32_e32 v52, v79, v79
	v_mul_f32_e32 v53, v77, v77
	v_pk_add_f32 v[66:67], v[36:37], v[48:49]
	v_mul_f32_e32 v36, v71, v71
	v_mul_f32_e32 v37, v69, v69
	v_mul_f32_e32 v54, v75, v75
	v_pk_add_f32 v[62:63], v[38:39], v[50:51]
	v_fmac_f32_e32 v52, v78, v78
	v_fmac_f32_e32 v53, v76, v76
	v_mul_f32_e32 v38, v67, v67
	v_fmac_f32_e32 v36, v70, v70
	v_fmac_f32_e32 v37, v68, v68
	v_mul_f32_e32 v55, v73, v73
	v_fmac_f32_e32 v54, v74, v74
	v_mul_f32_e32 v39, v63, v63
	v_add_f32_e32 v40, v52, v53
	v_fmac_f32_e32 v38, v66, v66
	v_add_f32_e32 v36, v36, v37
	v_fmac_f32_e32 v55, v72, v72
	v_add_f32_e32 v40, v54, v40
	v_add_f32_e32 v36, v36, v38
	v_fmac_f32_e32 v39, v62, v62
	v_add_f32_e32 v37, v55, v40
	v_add_f32_e32 v36, v39, v36
	v_add_f32_e32 v36, v36, v37
	ds_bpermute_b32 v37, v169, v36
	s_waitcnt lgkmcnt(0)
	v_add_f32_e32 v36, v36, v37
	ds_bpermute_b32 v37, v171, v36
	s_and_saveexec_b64 s[4:5], vcc
	s_cbranch_execz .LBB0_1388
	s_waitcnt lgkmcnt(0)
	v_add_f32_e32 v36, v36, v37
	ds_write_b32 v170, v36 offset:2304
.LBB0_1388:
	s_or_b64 exec, exec, s[4:5]
	s_waitcnt lgkmcnt(0)
	v_lshlrev_b64 v[36:37], 11, v[166:167]
	v_lshl_add_u64 v[36:37], s[42:43], 0, v[36:37]
	v_lshl_add_u64 v[36:37], v[0:1], 1, v[36:37]
	s_mov_b64 s[4:5], 0x50000
	v_lshl_add_u64 v[38:39], v[36:37], 0, s[4:5]
	v_lshl_add_u64 v[40:41], v[38:39], 0, v[162:163]
	v_lshl_add_u64 v[42:43], v[38:39], 0, v[164:165]
	v_mov_b32_e32 v46, 0
	v_mov_b32_e32 v47, 0
	v_mov_b32_e32 v48, 0
	v_mov_b32_e32 v49, 0
	s_waitcnt vmcnt(2)
	v_cndmask_b32_e64 v50, v224, v220, s[2:3]
	v_cndmask_b32_e64 v51, v225, v221, s[2:3]
	v_cndmask_b32_e64 v52, v226, v222, s[2:3]
	v_cndmask_b32_e64 v53, v227, v223, s[2:3]
	v_cndmask_b32_e64 v38, v220, v224, s[2:3]
	v_cndmask_b32_e64 v39, v221, v225, s[2:3]
	v_cndmask_b32_e64 v40, v222, v226, s[2:3]
	v_cndmask_b32_e64 v41, v223, v227, s[2:3]
	v_mov_b32_dpp v46, v38 row_ror:8 row_mask:0xf bank_mask:0xf
	v_mov_b32_dpp v47, v39 row_ror:8 row_mask:0xf bank_mask:0xf
	v_lshlrev_b32_e32 v42, 16, v52
	v_and_b32_e32 v43, 0xffff0000, v52
	v_lshlrev_b32_e32 v44, 16, v53
	v_and_b32_e32 v45, 0xffff0000, v53
	v_mov_b32_dpp v48, v40 row_ror:8 row_mask:0xf bank_mask:0xf
	v_mov_b32_dpp v49, v41 row_ror:8 row_mask:0xf bank_mask:0xf
	v_lshlrev_b32_e32 v38, 16, v50
	v_and_b32_e32 v39, 0xffff0000, v50
	v_lshlrev_b32_e32 v40, 16, v51
	v_and_b32_e32 v41, 0xffff0000, v51
	v_pk_add_f32 v[56:57], v[30:31], v[44:45]
	v_pk_add_f32 v[58:59], v[28:29], v[42:43]
	v_lshlrev_b32_e32 v28, 16, v46
	v_and_b32_e32 v29, 0xffff0000, v46
	v_lshlrev_b32_e32 v30, 16, v47
	v_and_b32_e32 v31, 0xffff0000, v47
	v_pk_add_f32 v[60:61], v[34:35], v[40:41]
	v_pk_add_f32 v[64:65], v[32:33], v[38:39]
	v_lshlrev_b32_e32 v32, 16, v48
	v_and_b32_e32 v33, 0xffff0000, v48
	v_pk_add_f32 v[52:53], v[26:27], v[30:31]
	v_pk_add_f32 v[54:55], v[24:25], v[28:29]
	v_lshlrev_b32_e32 v34, 16, v49
	v_and_b32_e32 v35, 0xffff0000, v49
	v_mul_f32_e32 v38, v65, v65
	v_mul_f32_e32 v39, v61, v61
	v_pk_add_f32 v[50:51], v[20:21], v[32:33]
	v_mul_f32_e32 v20, v55, v55
	v_mul_f32_e32 v21, v53, v53
	v_mul_f32_e32 v40, v59, v59
	v_pk_add_f32 v[48:49], v[22:23], v[34:35]
	v_fmac_f32_e32 v38, v64, v64
	v_fmac_f32_e32 v39, v60, v60
	v_mul_f32_e32 v22, v51, v51
	v_fmac_f32_e32 v20, v54, v54
	v_fmac_f32_e32 v21, v52, v52
	v_mul_f32_e32 v41, v57, v57
	v_fmac_f32_e32 v40, v58, v58
	v_mul_f32_e32 v23, v49, v49
	v_add_f32_e32 v24, v38, v39
	v_fmac_f32_e32 v22, v50, v50
	v_add_f32_e32 v20, v20, v21
	v_fmac_f32_e32 v41, v56, v56
	v_add_f32_e32 v24, v40, v24
	v_add_f32_e32 v20, v20, v22
	v_fmac_f32_e32 v23, v48, v48
	v_add_f32_e32 v21, v41, v24
	v_add_f32_e32 v20, v23, v20
	v_add_f32_e32 v20, v20, v21
	ds_bpermute_b32 v21, v169, v20
	s_waitcnt lgkmcnt(0)
	v_add_f32_e32 v21, v20, v21
	ds_bpermute_b32 v22, v171, v21
	v_mov_b32_e32 v20, 0
	s_and_saveexec_b64 s[4:5], vcc
	s_cbranch_execz .LBB0_1390
	s_waitcnt lgkmcnt(0)
	v_add_f32_e32 v21, v21, v22
	ds_write_b32 v170, v21 offset:2560
.LBB0_1390:
	s_or_b64 exec, exec, s[4:5]
	s_mov_b64 s[4:5], 0x58000
	s_waitcnt lgkmcnt(0)
	v_lshl_add_u64 v[22:23], v[36:37], 0, s[4:5]
	v_lshl_add_u64 v[24:25], v[22:23], 0, v[162:163]
	v_lshl_add_u64 v[26:27], v[22:23], 0, v[164:165]
	v_mov_b32_e32 v21, 0
	v_mov_b32_e32 v30, 0
	v_mov_b32_e32 v31, 0
	s_waitcnt vmcnt(0)
	v_cndmask_b32_e64 v32, v232, v228, s[2:3]
	v_cndmask_b32_e64 v33, v233, v229, s[2:3]
	v_cndmask_b32_e64 v34, v234, v230, s[2:3]
	v_cndmask_b32_e64 v35, v235, v231, s[2:3]
	v_cndmask_b32_e64 v22, v228, v232, s[2:3]
	v_cndmask_b32_e64 v23, v229, v233, s[2:3]
	v_cndmask_b32_e64 v24, v230, v234, s[2:3]
	v_cndmask_b32_e64 v25, v231, v235, s[2:3]
	v_mov_b32_dpp v21, v22 row_ror:8 row_mask:0xf bank_mask:0xf
	v_mov_b32_dpp v30, v23 row_ror:8 row_mask:0xf bank_mask:0xf
	v_lshlrev_b32_e32 v26, 16, v34
	v_and_b32_e32 v27, 0xffff0000, v34
	v_lshlrev_b32_e32 v28, 16, v35
	v_and_b32_e32 v29, 0xffff0000, v35
	v_mov_b32_dpp v31, v24 row_ror:8 row_mask:0xf bank_mask:0xf
	v_mov_b32_dpp v20, v25 row_ror:8 row_mask:0xf bank_mask:0xf
	v_lshlrev_b32_e32 v22, 16, v32
	v_and_b32_e32 v23, 0xffff0000, v32
	v_lshlrev_b32_e32 v24, 16, v33
	v_and_b32_e32 v25, 0xffff0000, v33
	v_pk_add_f32 v[40:41], v[14:15], v[28:29]
	v_pk_add_f32 v[42:43], v[12:13], v[26:27]
	v_lshlrev_b32_e32 v12, 16, v21
	v_and_b32_e32 v13, 0xffff0000, v21
	v_lshlrev_b32_e32 v14, 16, v30
	v_and_b32_e32 v15, 0xffff0000, v30
	v_pk_add_f32 v[44:45], v[18:19], v[24:25]
	v_pk_add_f32 v[46:47], v[16:17], v[22:23]
	v_lshlrev_b32_e32 v16, 16, v31
	v_and_b32_e32 v17, 0xffff0000, v31
	v_pk_add_f32 v[36:37], v[10:11], v[14:15]
	v_pk_add_f32 v[38:39], v[8:9], v[12:13]
	v_lshlrev_b32_e32 v18, 16, v20
	v_and_b32_e32 v19, 0xffff0000, v20
	v_mul_f32_e32 v20, v47, v47
	v_mul_f32_e32 v21, v45, v45
	v_pk_add_f32 v[34:35], v[4:5], v[16:17]
	v_mul_f32_e32 v4, v39, v39
	v_mul_f32_e32 v5, v37, v37
	v_mul_f32_e32 v22, v43, v43
	v_pk_add_f32 v[32:33], v[6:7], v[18:19]
	v_fmac_f32_e32 v20, v46, v46
	v_fmac_f32_e32 v21, v44, v44
	v_mul_f32_e32 v6, v35, v35
	v_fmac_f32_e32 v4, v38, v38
	v_fmac_f32_e32 v5, v36, v36
	v_mul_f32_e32 v23, v41, v41
	v_fmac_f32_e32 v22, v42, v42
	v_mul_f32_e32 v7, v33, v33
	v_add_f32_e32 v8, v20, v21
	v_fmac_f32_e32 v6, v34, v34
	v_add_f32_e32 v4, v4, v5
	v_fmac_f32_e32 v23, v40, v40
	v_add_f32_e32 v8, v22, v8
	v_add_f32_e32 v4, v4, v6
	v_fmac_f32_e32 v7, v32, v32
	v_add_f32_e32 v5, v23, v8
	v_add_f32_e32 v4, v7, v4
	v_add_f32_e32 v4, v4, v5
	ds_bpermute_b32 v5, v169, v4
	s_waitcnt lgkmcnt(0)
	v_add_f32_e32 v4, v4, v5
	ds_bpermute_b32 v5, v171, v4
	s_and_saveexec_b64 s[4:5], vcc
	s_cbranch_execz .LBB0_1392
	s_waitcnt lgkmcnt(0)
	v_add_f32_e32 v4, v4, v5
	ds_write_b32 v170, v4 offset:2816
